# kernel start-up: the 18 dependent load/compute/write rounds of the conditioning silu become 18 loads issued together and one wait
# baseline (speedup 1.0000x reference)
; #define LAS __attribute__((address_space(3)))
; __device__ __forceinline__ int tid_() { int t = threadIdx.x; asm volatile("" : "+v"(t)); return t; }
; __device__ __forceinline__ int bid_() { int t = blockIdx.x; asm volatile("" : "+s"(t)); return t; }
; __device__ __forceinline__ void phase_pre(KArgs& a, LAS unsigned char* lds) {
;     const int tid = tid_(), bid = bid_();
;     {
;         LAS float* s = (LAS float*)lds;
;         LAS float* red = (LAS float*)(lds + 36864);
;         for (int i = tid; i < 9 * 1024; i += 512) { const int j = i >> 10, k = i & 1023; const float v = (j < 8) ? a.c[j * 1024 + k] : a.c_ctx[k]; s[i] = v / (1.f + __expf(-v)); }
;         __syncthreads();
.LBB0_5:
	s_or_b64 exec, exec, s[0:1]
	s_cmp_lt_i32 s50, 1
	s_cselect_b64 s[0:1], -1, 0
	s_cmp_gt_i32 s51, 0
	s_cselect_b64 s[4:5], -1, 0
	s_and_b64 s[0:1], s[0:1], s[4:5]
	s_andn2_b64 vcc, exec, s[0:1]
	s_mov_b32 s87, 1
	s_cbranch_vccnz .LBB0_94
	s_mov_b64 s[20:21], s[58:59]
	s_mov_b32 s0, 0
	s_mov_b32 s0, s56
	s_mov_b32 s1, s84
	v_mov_b32_e32 v34, v216
	s_movk_i32 s0, 0x2400
	s_mov_b32 s22, s84
	v_cmp_gt_i32_e32 vcc, s0, v34
	v_ashrrev_i32_e32 v35, 31, v34
	v_lshl_add_u32 v6, v34, 2, 0
	s_and_saveexec_b64 s[0:1], vcc
	s_cbranch_execz .LBB0_9
	s_load_dwordx2 s[8:9], s[20:21], 0x8
	s_load_dwordx2 s[4:5], s[20:21], 0x18
	v_mov_b32_e32 v3, 0
	v_mov_b32_e32 v1, v6
	v_lshlrev_b32_e32 v2, 2, v34
	s_waitcnt lgkmcnt(0)
	global_load_dword v40, v2, s[8:9]
	global_load_dword v41, v2, s[8:9] offset:2048
	v_add_u32_e32 v4, 0x1000, v2
	global_load_dword v42, v4, s[8:9]
	global_load_dword v43, v4, s[8:9] offset:2048
	v_add_u32_e32 v4, 0x2000, v2
	global_load_dword v44, v4, s[8:9]
	global_load_dword v45, v4, s[8:9] offset:2048
	v_add_u32_e32 v4, 0x3000, v2
	global_load_dword v46, v4, s[8:9]
	global_load_dword v47, v4, s[8:9] offset:2048
	v_add_u32_e32 v4, 0x4000, v2
	global_load_dword v48, v4, s[8:9]
	global_load_dword v49, v4, s[8:9] offset:2048
	v_add_u32_e32 v4, 0x5000, v2
	global_load_dword v50, v4, s[8:9]
	global_load_dword v51, v4, s[8:9] offset:2048
	v_add_u32_e32 v4, 0x6000, v2
	global_load_dword v52, v4, s[8:9]
	global_load_dword v53, v4, s[8:9] offset:2048
	v_add_u32_e32 v4, 0x7000, v2
	global_load_dword v54, v4, s[8:9]
	global_load_dword v55, v4, s[8:9] offset:2048
	global_load_dword v56, v2, s[4:5]
	global_load_dword v57, v2, s[4:5] offset:2048
	s_waitcnt vmcnt(17)
	v_mul_f32_e32 v8, 0xbfb8aa3b, v40
	v_exp_f32_e32 v8, v8
	s_nop 0
	v_add_f32_e32 v8, 1.0, v8
	v_div_scale_f32 v9, s[14:15], v8, v8, v40
	v_rcp_f32_e32 v10, v9
	v_div_scale_f32 v11, vcc, v40, v8, v40
	v_fma_f32 v12, -v9, v10, 1.0
	v_fmac_f32_e32 v10, v12, v10
	v_mul_f32_e32 v12, v11, v10
	v_fma_f32 v13, -v9, v12, v11
	v_fmac_f32_e32 v12, v13, v10
	v_fma_f32 v9, -v9, v12, v11
	v_div_fmas_f32 v9, v9, v10, v12
	v_div_fixup_f32 v40, v9, v8, v40
	ds_write_b32 v1, v40
	s_waitcnt vmcnt(16)
	v_mul_f32_e32 v8, 0xbfb8aa3b, v41
	v_exp_f32_e32 v8, v8
	s_nop 0
	v_add_f32_e32 v8, 1.0, v8
	v_div_scale_f32 v9, s[14:15], v8, v8, v41
	v_rcp_f32_e32 v10, v9
	v_div_scale_f32 v11, vcc, v41, v8, v41
	v_fma_f32 v12, -v9, v10, 1.0
	v_fmac_f32_e32 v10, v12, v10
	v_mul_f32_e32 v12, v11, v10
	v_fma_f32 v13, -v9, v12, v11
	v_fmac_f32_e32 v12, v13, v10
	v_fma_f32 v9, -v9, v12, v11
	v_div_fmas_f32 v9, v9, v10, v12
	v_div_fixup_f32 v41, v9, v8, v41
	ds_write_b32 v1, v41 offset:2048
	s_waitcnt vmcnt(15)
	v_mul_f32_e32 v8, 0xbfb8aa3b, v42
	v_exp_f32_e32 v8, v8
	s_nop 0
	v_add_f32_e32 v8, 1.0, v8
	v_div_scale_f32 v9, s[14:15], v8, v8, v42
	v_rcp_f32_e32 v10, v9
	v_div_scale_f32 v11, vcc, v42, v8, v42
	v_fma_f32 v12, -v9, v10, 1.0
	v_fmac_f32_e32 v10, v12, v10
	v_mul_f32_e32 v12, v11, v10
	v_fma_f32 v13, -v9, v12, v11
	v_fmac_f32_e32 v12, v13, v10
	v_fma_f32 v9, -v9, v12, v11
	v_div_fmas_f32 v9, v9, v10, v12
	v_div_fixup_f32 v42, v9, v8, v42
	ds_write_b32 v1, v42 offset:4096
	s_waitcnt vmcnt(14)
	v_mul_f32_e32 v8, 0xbfb8aa3b, v43
	v_exp_f32_e32 v8, v8
	s_nop 0
	v_add_f32_e32 v8, 1.0, v8
	v_div_scale_f32 v9, s[14:15], v8, v8, v43
	v_rcp_f32_e32 v10, v9
	v_div_scale_f32 v11, vcc, v43, v8, v43
	v_fma_f32 v12, -v9, v10, 1.0
	v_fmac_f32_e32 v10, v12, v10
	v_mul_f32_e32 v12, v11, v10
	v_fma_f32 v13, -v9, v12, v11
	v_fmac_f32_e32 v12, v13, v10
	v_fma_f32 v9, -v9, v12, v11
	v_div_fmas_f32 v9, v9, v10, v12
	v_div_fixup_f32 v43, v9, v8, v43
	ds_write_b32 v1, v43 offset:6144
	s_waitcnt vmcnt(13)
	v_mul_f32_e32 v8, 0xbfb8aa3b, v44
	v_exp_f32_e32 v8, v8
	s_nop 0
	v_add_f32_e32 v8, 1.0, v8
	v_div_scale_f32 v9, s[14:15], v8, v8, v44
	v_rcp_f32_e32 v10, v9
	v_div_scale_f32 v11, vcc, v44, v8, v44
	v_fma_f32 v12, -v9, v10, 1.0
	v_fmac_f32_e32 v10, v12, v10
	v_mul_f32_e32 v12, v11, v10
	v_fma_f32 v13, -v9, v12, v11
	v_fmac_f32_e32 v12, v13, v10
	v_fma_f32 v9, -v9, v12, v11
	v_div_fmas_f32 v9, v9, v10, v12
	v_div_fixup_f32 v44, v9, v8, v44
	ds_write_b32 v1, v44 offset:8192
	s_waitcnt vmcnt(12)
	v_mul_f32_e32 v8, 0xbfb8aa3b, v45
	v_exp_f32_e32 v8, v8
	s_nop 0
	v_add_f32_e32 v8, 1.0, v8
	v_div_scale_f32 v9, s[14:15], v8, v8, v45
	v_rcp_f32_e32 v10, v9
	v_div_scale_f32 v11, vcc, v45, v8, v45
	v_fma_f32 v12, -v9, v10, 1.0
	v_fmac_f32_e32 v10, v12, v10
	v_mul_f32_e32 v12, v11, v10
	v_fma_f32 v13, -v9, v12, v11
	v_fmac_f32_e32 v12, v13, v10
	v_fma_f32 v9, -v9, v12, v11
	v_div_fmas_f32 v9, v9, v10, v12
	v_div_fixup_f32 v45, v9, v8, v45
	ds_write_b32 v1, v45 offset:10240
	s_waitcnt vmcnt(11)
	v_mul_f32_e32 v8, 0xbfb8aa3b, v46
	v_exp_f32_e32 v8, v8
	s_nop 0
	v_add_f32_e32 v8, 1.0, v8
	v_div_scale_f32 v9, s[14:15], v8, v8, v46
	v_rcp_f32_e32 v10, v9
	v_div_scale_f32 v11, vcc, v46, v8, v46
	v_fma_f32 v12, -v9, v10, 1.0
	v_fmac_f32_e32 v10, v12, v10
	v_mul_f32_e32 v12, v11, v10
	v_fma_f32 v13, -v9, v12, v11
	v_fmac_f32_e32 v12, v13, v10
	v_fma_f32 v9, -v9, v12, v11
	v_div_fmas_f32 v9, v9, v10, v12
	v_div_fixup_f32 v46, v9, v8, v46
	ds_write_b32 v1, v46 offset:12288
	s_waitcnt vmcnt(10)
; __device__ __forceinline__ void phase_pre(KArgs& a, LAS unsigned char* lds) {
;     ...
;         for (int i = tid; i < 9 * 1024; i += 512) { const int j = i >> 10, k = i & 1023; const float v = (j < 8) ? a.c[j * 1024 + k] : a.c_ctx[k]; s[i] = v / (1.f + __expf(-v)); }
;         __syncthreads();
	v_mul_f32_e32 v8, 0xbfb8aa3b, v47
	v_exp_f32_e32 v8, v8
	s_nop 0
	v_add_f32_e32 v8, 1.0, v8
	v_div_scale_f32 v9, s[14:15], v8, v8, v47
	v_rcp_f32_e32 v10, v9
	v_div_scale_f32 v11, vcc, v47, v8, v47
	v_fma_f32 v12, -v9, v10, 1.0
	v_fmac_f32_e32 v10, v12, v10
	v_mul_f32_e32 v12, v11, v10
	v_fma_f32 v13, -v9, v12, v11
	v_fmac_f32_e32 v12, v13, v10
	v_fma_f32 v9, -v9, v12, v11
	v_div_fmas_f32 v9, v9, v10, v12
	v_div_fixup_f32 v47, v9, v8, v47
	ds_write_b32 v1, v47 offset:14336
	s_waitcnt vmcnt(9)
	v_mul_f32_e32 v8, 0xbfb8aa3b, v48
	v_exp_f32_e32 v8, v8
	s_nop 0
	v_add_f32_e32 v8, 1.0, v8
	v_div_scale_f32 v9, s[14:15], v8, v8, v48
	v_rcp_f32_e32 v10, v9
	v_div_scale_f32 v11, vcc, v48, v8, v48
	v_fma_f32 v12, -v9, v10, 1.0
	v_fmac_f32_e32 v10, v12, v10
	v_mul_f32_e32 v12, v11, v10
	v_fma_f32 v13, -v9, v12, v11
	v_fmac_f32_e32 v12, v13, v10
	v_fma_f32 v9, -v9, v12, v11
	v_div_fmas_f32 v9, v9, v10, v12
	v_div_fixup_f32 v48, v9, v8, v48
	ds_write_b32 v1, v48 offset:16384
	s_waitcnt vmcnt(8)
	v_mul_f32_e32 v8, 0xbfb8aa3b, v49
	v_exp_f32_e32 v8, v8
	s_nop 0
	v_add_f32_e32 v8, 1.0, v8
	v_div_scale_f32 v9, s[14:15], v8, v8, v49
	v_rcp_f32_e32 v10, v9
	v_div_scale_f32 v11, vcc, v49, v8, v49
	v_fma_f32 v12, -v9, v10, 1.0
	v_fmac_f32_e32 v10, v12, v10
	v_mul_f32_e32 v12, v11, v10
	v_fma_f32 v13, -v9, v12, v11
	v_fmac_f32_e32 v12, v13, v10
	v_fma_f32 v9, -v9, v12, v11
	v_div_fmas_f32 v9, v9, v10, v12
	v_div_fixup_f32 v49, v9, v8, v49
	ds_write_b32 v1, v49 offset:18432
	s_waitcnt vmcnt(7)
	v_mul_f32_e32 v8, 0xbfb8aa3b, v50
	v_exp_f32_e32 v8, v8
	s_nop 0
	v_add_f32_e32 v8, 1.0, v8
	v_div_scale_f32 v9, s[14:15], v8, v8, v50
	v_rcp_f32_e32 v10, v9
	v_div_scale_f32 v11, vcc, v50, v8, v50
	v_fma_f32 v12, -v9, v10, 1.0
	v_fmac_f32_e32 v10, v12, v10
	v_mul_f32_e32 v12, v11, v10
	v_fma_f32 v13, -v9, v12, v11
	v_fmac_f32_e32 v12, v13, v10
	v_fma_f32 v9, -v9, v12, v11
	v_div_fmas_f32 v9, v9, v10, v12
	v_div_fixup_f32 v50, v9, v8, v50
	ds_write_b32 v1, v50 offset:20480
	s_waitcnt vmcnt(6)
	v_mul_f32_e32 v8, 0xbfb8aa3b, v51
	v_exp_f32_e32 v8, v8
	s_nop 0
	v_add_f32_e32 v8, 1.0, v8
	v_div_scale_f32 v9, s[14:15], v8, v8, v51
	v_rcp_f32_e32 v10, v9
	v_div_scale_f32 v11, vcc, v51, v8, v51
	v_fma_f32 v12, -v9, v10, 1.0
	v_fmac_f32_e32 v10, v12, v10
	v_mul_f32_e32 v12, v11, v10
	v_fma_f32 v13, -v9, v12, v11
	v_fmac_f32_e32 v12, v13, v10
	v_fma_f32 v9, -v9, v12, v11
	v_div_fmas_f32 v9, v9, v10, v12
	v_div_fixup_f32 v51, v9, v8, v51
	ds_write_b32 v1, v51 offset:22528
	s_waitcnt vmcnt(5)
	v_mul_f32_e32 v8, 0xbfb8aa3b, v52
	v_exp_f32_e32 v8, v8
	s_nop 0
	v_add_f32_e32 v8, 1.0, v8
	v_div_scale_f32 v9, s[14:15], v8, v8, v52
	v_rcp_f32_e32 v10, v9
	v_div_scale_f32 v11, vcc, v52, v8, v52
	v_fma_f32 v12, -v9, v10, 1.0
	v_fmac_f32_e32 v10, v12, v10
	v_mul_f32_e32 v12, v11, v10
	v_fma_f32 v13, -v9, v12, v11
	v_fmac_f32_e32 v12, v13, v10
	v_fma_f32 v9, -v9, v12, v11
	v_div_fmas_f32 v9, v9, v10, v12
	v_div_fixup_f32 v52, v9, v8, v52
	ds_write_b32 v1, v52 offset:24576
	s_waitcnt vmcnt(4)
	v_mul_f32_e32 v8, 0xbfb8aa3b, v53
	v_exp_f32_e32 v8, v8
	s_nop 0
	v_add_f32_e32 v8, 1.0, v8
	v_div_scale_f32 v9, s[14:15], v8, v8, v53
	v_rcp_f32_e32 v10, v9
	v_div_scale_f32 v11, vcc, v53, v8, v53
	v_fma_f32 v12, -v9, v10, 1.0
	v_fmac_f32_e32 v10, v12, v10
	v_mul_f32_e32 v12, v11, v10
	v_fma_f32 v13, -v9, v12, v11
	v_fmac_f32_e32 v12, v13, v10
	v_fma_f32 v9, -v9, v12, v11
	v_div_fmas_f32 v9, v9, v10, v12
	v_div_fixup_f32 v53, v9, v8, v53
	ds_write_b32 v1, v53 offset:26624
	s_waitcnt vmcnt(3)
	v_mul_f32_e32 v8, 0xbfb8aa3b, v54
	v_exp_f32_e32 v8, v8
	s_nop 0
	v_add_f32_e32 v8, 1.0, v8
	v_div_scale_f32 v9, s[14:15], v8, v8, v54
	v_rcp_f32_e32 v10, v9
	v_div_scale_f32 v11, vcc, v54, v8, v54
	v_fma_f32 v12, -v9, v10, 1.0
	v_fmac_f32_e32 v10, v12, v10
	v_mul_f32_e32 v12, v11, v10
	v_fma_f32 v13, -v9, v12, v11
	v_fmac_f32_e32 v12, v13, v10
	v_fma_f32 v9, -v9, v12, v11
	v_div_fmas_f32 v9, v9, v10, v12
	v_div_fixup_f32 v54, v9, v8, v54
	ds_write_b32 v1, v54 offset:28672
	s_waitcnt vmcnt(2)
	v_mul_f32_e32 v8, 0xbfb8aa3b, v55
	v_exp_f32_e32 v8, v8
	s_nop 0
	v_add_f32_e32 v8, 1.0, v8
	v_div_scale_f32 v9, s[14:15], v8, v8, v55
	v_rcp_f32_e32 v10, v9
	v_div_scale_f32 v11, vcc, v55, v8, v55
	v_fma_f32 v12, -v9, v10, 1.0
	v_fmac_f32_e32 v10, v12, v10
	v_mul_f32_e32 v12, v11, v10
	v_fma_f32 v13, -v9, v12, v11
	v_fmac_f32_e32 v12, v13, v10
	v_fma_f32 v9, -v9, v12, v11
	v_div_fmas_f32 v9, v9, v10, v12
	v_div_fixup_f32 v55, v9, v8, v55
	ds_write_b32 v1, v55 offset:30720
	s_waitcnt vmcnt(1)
	v_mul_f32_e32 v8, 0xbfb8aa3b, v56
	v_exp_f32_e32 v8, v8
	s_nop 0
	v_add_f32_e32 v8, 1.0, v8
	v_div_scale_f32 v9, s[14:15], v8, v8, v56
	v_rcp_f32_e32 v10, v9
	v_div_scale_f32 v11, vcc, v56, v8, v56
	v_fma_f32 v12, -v9, v10, 1.0
	v_fmac_f32_e32 v10, v12, v10
	v_mul_f32_e32 v12, v11, v10
	v_fma_f32 v13, -v9, v12, v11
	v_fmac_f32_e32 v12, v13, v10
	v_fma_f32 v9, -v9, v12, v11
	v_div_fmas_f32 v9, v9, v10, v12
	v_div_fixup_f32 v56, v9, v8, v56
	ds_write_b32 v1, v56 offset:32768
	s_waitcnt vmcnt(0)
	v_mul_f32_e32 v8, 0xbfb8aa3b, v57
	v_exp_f32_e32 v8, v8
	s_nop 0
	v_add_f32_e32 v8, 1.0, v8
	v_div_scale_f32 v9, s[14:15], v8, v8, v57
	v_rcp_f32_e32 v10, v9
	v_div_scale_f32 v11, vcc, v57, v8, v57
	v_fma_f32 v12, -v9, v10, 1.0
	v_fmac_f32_e32 v10, v12, v10
	v_mul_f32_e32 v12, v11, v10
	v_fma_f32 v13, -v9, v12, v11
	v_fmac_f32_e32 v12, v13, v10
	v_fma_f32 v9, -v9, v12, v11
	v_div_fmas_f32 v9, v9, v10, v12
	v_div_fixup_f32 v57, v9, v8, v57
	ds_write_b32 v1, v57 offset:34816
